# speedup vs baseline: 1.0260x; 1.0260x over previous
.LBB0_192:
	s_and_b32 s22, s6, 3
	s_lshl_b32 s52, s7, 6
	s_lshl_b32 s20, s7, 13
	s_mov_b64 s[6:7], 0x80
	s_add_i32 m0, s33, 0x18000
	v_lshl_add_u64 v[6:7], v[6:7], 0, s[6:7]
	s_lshl_b32 s53, s22, 5
	s_lshl_b32 s21, s22, 12
	global_load_lds_dwordx4 v[6:7], off
	v_lshl_add_u64 v[2:3], v[2:3], 0, s[6:7]
	s_add_i32 m0, s33, 0x1a000
	s_add_i32 s65, s33, 0x8000
	s_add_i32 s72, s33, 0xa000
	global_load_lds_dwordx4 v[2:3], off
	v_lshl_add_u64 v[0:1], v[0:1], 0, s[6:7]
	s_mov_b32 m0, s65
	s_add_u32 s18, s54, 0x80080
	global_load_lds_dwordx4 v[0:1], off
	v_lshl_add_u64 v[0:1], v[4:5], 0, s[6:7]
	s_mov_b32 m0, s72
	s_addc_u32 s19, s55, 0
	global_load_lds_dwordx4 v[0:1], off
	s_add_i32 m0, s33, 0x1c000
	v_lshl_add_u64 v[0:1], s[18:19], 0, v[134:135]
	global_load_lds_dwordx4 v[0:1], off
	v_lshl_add_u64 v[0:1], s[18:19], 0, v[138:139]
	s_add_i32 m0, s33, 0x1e000
	s_movk_i32 s18, 0x3c0
	global_load_lds_dwordx4 v[0:1], off
	s_waitcnt vmcnt(8)
	s_barrier
	v_and_b32_e32 v0, 48, v150
	v_lshlrev_b32_e32 v1, 6, v150
	v_and_or_b32 v0, v1, s18, v0
	v_lshlrev_b32_e32 v1, 2, v150
	v_and_b32_e32 v1, 32, v1
	v_bitop3_b32 v2, v0, s20, v1 bitop3:0xde
	v_bitop3_b32 v151, v0, s21, v1 bitop3:0xde
	v_lshlrev_b32_e32 v0, 15, v8
	v_and_b32_e32 v0, 0xffff0000, v0
	v_lshl_add_u32 v0, v9, 12, v0
	v_and_b32_e32 v1, 1, v8
	s_cmpk_lt_u32 s2, 0x100
	v_lshl_or_b32 v0, v1, 6, v0
	s_cselect_b64 s[18:19], -1, 0
	s_cmp_lt_u32 s22, 2
	v_lshl_add_u32 v142, v10, 1, v0
	v_lshlrev_b32_e32 v0, 15, v11
	s_cselect_b64 s[20:21], -1, 0
	s_lshl_b32 s73, s22, 4
	s_lshl_b32 s2, s22, 6
	v_and_b32_e32 v0, 0xffff0000, v0
	s_waitcnt vmcnt(6)
	s_add_u32 s22, s93, s2
	v_readlane_b32 s2, v252, 31
	v_lshl_add_u32 v0, v12, 12, v0
	v_and_b32_e32 v1, 1, v11
	s_addc_u32 s23, s2, 0
	v_lshl_or_b32 v0, v1, 6, v0
	s_add_i32 s74, 0, 0x10000
	s_add_i32 s75, 0, 0x14000
	v_mov_b32_e32 v143, v141
	v_lshl_add_u32 v144, v13, 1, v0
	v_mov_b32_e32 v145, v141
	v_add_u32_e32 v152, s74, v151
	v_add_u32_e32 v153, s75, v151
	v_add_u32_e32 v154, 0, v2
	s_movk_i32 s84, 0x1800
	v_mbcnt_hi_u32_b32 v155, -1, v219
	v_mov_b32_e32 v156, 0x3e0293ee
	s_barrier
	s_branch .LBB0_195

.LBB0_304:
	s_and_b64 s[20:21], s[0:1], exec
	s_cselect_b32 s42, s62, 64
	s_and_b32 s6, s6, 3
	s_lshl_b32 s43, s7, 6
	s_lshl_b32 s22, s7, 13
	s_lshl_b32 s46, s6, 5
	s_lshl_b32 s23, s6, 12
	s_mov_b64 s[6:7], 0x80
	s_add_i32 m0, s2, 0x18000
	v_lshl_add_u64 v[6:7], v[6:7], 0, s[6:7]
	global_load_lds_dwordx4 v[6:7], off
	v_lshl_add_u64 v[2:3], v[2:3], 0, s[6:7]
	s_add_i32 m0, s2, 0x1a000
	s_add_i32 s47, s2, 0x8000
	s_add_i32 s48, s2, 0xa000
	global_load_lds_dwordx4 v[2:3], off
	v_lshl_add_u64 v[0:1], v[0:1], 0, s[6:7]
	s_mov_b32 m0, s47
	s_add_u32 s20, s38, 0x80080
	global_load_lds_dwordx4 v[0:1], off
	v_lshl_add_u64 v[0:1], v[4:5], 0, s[6:7]
	s_mov_b32 m0, s48
	s_addc_u32 s21, s39, 0
	global_load_lds_dwordx4 v[0:1], off
	s_add_i32 m0, s2, 0x1c000
	v_lshl_add_u64 v[0:1], s[20:21], 0, v[130:131]
	global_load_lds_dwordx4 v[0:1], off
	v_lshl_add_u64 v[0:1], s[20:21], 0, v[134:135]
	s_add_i32 m0, s2, 0x1e000
	s_sext_i32_i8 s52, s18
	global_load_lds_dwordx4 v[0:1], off
	s_waitcnt vmcnt(8)
	s_barrier
	v_and_b32_e32 v0, 48, v144
	v_lshlrev_b32_e32 v1, 6, v144
	s_movk_i32 s18, 0x3c0
	v_and_or_b32 v0, v1, s18, v0
	v_lshlrev_b32_e32 v1, 2, v144
	v_and_b32_e32 v1, 32, v1
	v_bitop3_b32 v2, v0, s22, v1 bitop3:0xde
	v_bitop3_b32 v145, v0, s23, v1 bitop3:0xde
	v_lshlrev_b32_e32 v0, 15, v8
	v_and_b32_e32 v0, 0xffff0000, v0
	v_lshl_add_u32 v0, v9, 12, v0
	v_and_b32_e32 v1, 1, v8
	v_lshl_or_b32 v0, v1, 6, v0
	v_lshl_add_u32 v138, v10, 1, v0
	v_lshlrev_b32_e32 v0, 15, v11
	v_and_b32_e32 v0, 0xffff0000, v0
	s_waitcnt vmcnt(6)
	s_cmpk_lt_u32 s19, 0x100
	v_lshl_add_u32 v0, v12, 12, v0
	v_and_b32_e32 v1, 1, v11
	s_cselect_b64 s[18:19], -1, 0
	v_lshl_or_b32 v0, v1, 6, v0
	s_add_i32 s49, 0, 0x10000
	s_add_i32 s50, 0, 0x14000
	v_mov_b32_e32 v139, v137
	v_lshl_add_u32 v140, v13, 1, v0
	v_mov_b32_e32 v141, v137
	v_add_u32_e32 v146, s49, v145
	v_add_u32_e32 v147, s50, v145
	v_add_u32_e32 v148, 0, v2
	s_mov_b64 s[24:25], s[36:37]
	s_mov_b64 s[26:27], s[38:39]
	s_barrier
	s_branch .LBB0_307

.LBB0_328:
	v_and_b32_e32 v14, 48, v156
	v_lshlrev_b32_e32 v15, 6, v156
	s_movk_i32 s5, 0x3c0
	v_and_or_b32 v14, v15, s5, v14
	v_lshlrev_b32_e32 v15, 2, v156
	s_lshl_b32 s53, s0, 6
	s_lshl_b32 s0, s0, 13
	v_and_b32_e32 v15, 32, v15
	v_bitop3_b32 v16, v14, s0, v15 bitop3:0xde
	s_lshl_b32 s0, s1, 5
	s_mov_b64 s[20:21], 0x80
	s_and_b32 s55, s0, 0x60
	s_add_i32 m0, s39, 0x18000
	v_lshl_add_u64 v[6:7], v[6:7], 0, s[20:21]
	s_lshl_b32 s0, s55, 7
	global_load_lds_dwordx4 v[6:7], off
	v_lshl_add_u64 v[4:5], v[4:5], 0, s[20:21]
	s_add_i32 m0, s39, 0x1a000
	s_add_i32 s65, s39, 0x8000
	s_add_i32 s66, s39, 0xa000
	v_bitop3_b32 v157, s0, v14, v15 bitop3:0xf6
	global_load_lds_dwordx4 v[4:5], off
	v_lshl_add_u64 v[0:1], v[0:1], 0, s[20:21]
	s_mov_b32 m0, s65
	s_add_u32 s0, s6, 0x20080
	global_load_lds_dwordx4 v[0:1], off
	v_lshl_add_u64 v[0:1], v[2:3], 0, s[20:21]
	s_mov_b32 m0, s66
	s_addc_u32 s1, s7, 0
	global_load_lds_dwordx4 v[0:1], off
	s_add_i32 m0, s39, 0x1c000
	v_lshl_add_u64 v[0:1], s[0:1], 0, v[130:131]
	global_load_lds_dwordx4 v[0:1], off
	v_lshl_add_u64 v[0:1], s[0:1], 0, v[134:135]
	s_add_i32 m0, s39, 0x1e000
	s_cmpk_lt_u32 s3, 0x100
	global_load_lds_dwordx4 v[0:1], off
	s_waitcnt vmcnt(8)
	s_barrier
	v_lshlrev_b32_e32 v0, 13, v8
	v_and_b32_e32 v0, 0xffffc000, v0
	v_lshl_add_u32 v0, v9, 10, v0
	v_and_b32_e32 v1, 1, v8
	v_lshl_or_b32 v0, v1, 6, v0
	v_lshl_add_u32 v138, v10, 1, v0
	v_lshlrev_b32_e32 v0, 13, v11
	v_and_b32_e32 v0, 0xffffc000, v0
	s_waitcnt vmcnt(6)
	v_lshl_add_u32 v0, v12, 10, v0
	v_and_b32_e32 v1, 1, v11
	s_cselect_b64 s[22:23], -1, 0
	v_lshl_or_b32 v0, v1, 6, v0
	s_add_i32 s74, 0, 0x10000
	s_add_i32 s75, 0, 0x14000
	v_mov_b32_e32 v139, v137
	v_lshl_add_u32 v140, v13, 1, v0
	v_mov_b32_e32 v141, v137
	s_mov_b32 s67, 0x2aaaaaab
	v_add_u32_e32 v158, s74, v157
	v_add_u32_e32 v159, s75, v157
	v_add_u32_e32 v160, 0, v16
	s_movk_i32 s84, 0x7f
	s_movk_i32 s85, 0xc00
	v_mov_b32_e32 v161, 0x358637bd
	s_mov_b32 s86, 0x800000
	s_mov_b64 s[30:31], s[6:7]
	s_mov_b64 s[26:27], s[36:37]
	s_barrier
	s_branch .LBB0_331

.LBB0_386:
	s_lshl_b32 s51, s10, 6
	s_lshl_b32 s14, s10, 13
	s_lshl_b32 s10, s11, 5
	s_and_b32 s52, s10, 0x60
	s_mov_b64 s[10:11], 0x80
	s_add_i32 m0, s21, 0x18000
	v_lshl_add_u64 v[6:7], v[6:7], 0, s[10:11]
	s_lshl_b32 s15, s52, 7
	global_load_lds_dwordx4 v[6:7], off
	v_lshl_add_u64 v[4:5], v[4:5], 0, s[10:11]
	s_add_i32 m0, s21, 0x1a000
	s_add_i32 s53, s21, 0x8000
	s_add_i32 s55, s21, 0xa000
	global_load_lds_dwordx4 v[4:5], off
	v_lshl_add_u64 v[0:1], v[0:1], 0, s[10:11]
	s_mov_b32 m0, s53
	s_add_u32 s12, s34, 0x10080
	global_load_lds_dwordx4 v[0:1], off
	v_lshl_add_u64 v[0:1], v[2:3], 0, s[10:11]
	s_mov_b32 m0, s55
	s_addc_u32 s13, s35, 0
	global_load_lds_dwordx4 v[0:1], off
	s_add_i32 m0, s21, 0x1c000
	v_lshl_add_u64 v[0:1], s[12:13], 0, v[134:135]
	global_load_lds_dwordx4 v[0:1], off
	v_lshl_add_u64 v[0:1], s[12:13], 0, v[138:139]
	s_add_i32 m0, s21, 0x1e000
	s_movk_i32 s12, 0x3c0
	global_load_lds_dwordx4 v[0:1], off
	s_waitcnt vmcnt(8)
	s_barrier
	v_and_b32_e32 v0, 48, v164
	v_lshlrev_b32_e32 v1, 6, v164
	v_and_or_b32 v0, v1, s12, v0
	v_lshlrev_b32_e32 v1, 2, v164
	v_and_b32_e32 v1, 32, v1
	s_waitcnt vmcnt(6)
	s_cmpk_lt_u32 s3, 0x100
	v_bitop3_b32 v2, v0, s14, v1 bitop3:0xde
	v_bitop3_b32 v165, s15, v0, v1 bitop3:0xf6
	s_cselect_b64 s[12:13], -1, 0
	s_add_i32 s33, s33, s54
	s_add_i32 s67, 0, 0x10000
	s_add_i32 s74, 0, 0x14000
	s_lshl_b32 s65, s33, 5
	s_lshl_b32 s66, s54, 5
	v_add_u32_e32 v166, s67, v165
	v_add_u32_e32 v167, s74, v165
	v_add_u32_e32 v168, 0, v2
	s_mov_b64 s[14:15], 0x100
	s_mov_b64 s[16:17], 0x180
	s_mov_b32 s18, 0x3b800000
	s_mov_b32 s75, 0x800000
	s_mov_b32 s20, 0x45800000
	v_mov_b32_e32 v169, 0x358637bd
	s_barrier
	s_branch .LBB0_389

.LBB0_468:
	s_lshl_b32 s31, s4, 6
	s_lshl_b32 s7, s4, 13
	s_lshl_b32 s4, s5, 5
	s_and_b32 s33, s4, 0x60
	s_mov_b64 s[4:5], 0x80
	s_add_i32 m0, s24, 0x18000
	v_lshl_add_u64 v[6:7], v[6:7], 0, s[4:5]
	s_ashr_i32 s43, s70, 7
	s_lshl_b32 s10, s33, 7
	global_load_lds_dwordx4 v[6:7], off
	v_lshl_add_u64 v[4:5], v[4:5], 0, s[4:5]
	s_add_i32 m0, s24, 0x1a000
	s_add_i32 s34, s24, 0x8000
	s_add_i32 s35, s24, 0xa000
	global_load_lds_dwordx4 v[4:5], off
	v_lshl_add_u64 v[0:1], v[0:1], 0, s[4:5]
	s_mov_b32 m0, s34
	s_add_u32 s8, s18, 0x80080
	global_load_lds_dwordx4 v[0:1], off
	v_lshl_add_u64 v[0:1], v[2:3], 0, s[4:5]
	s_mov_b32 m0, s35
	s_addc_u32 s9, s19, 0
	global_load_lds_dwordx4 v[0:1], off
	s_add_i32 m0, s24, 0x1c000
	v_lshl_add_u64 v[0:1], s[8:9], 0, v[134:135]
	global_load_lds_dwordx4 v[0:1], off
	v_lshl_add_u64 v[0:1], s[8:9], 0, v[138:139]
	s_add_i32 m0, s24, 0x1e000
	s_movk_i32 s8, 0x3c0
	global_load_lds_dwordx4 v[0:1], off
	s_waitcnt vmcnt(8)
	s_barrier
	v_and_b32_e32 v0, 48, v158
	v_lshlrev_b32_e32 v1, 6, v158
	v_and_or_b32 v0, v1, s8, v0
	v_lshlrev_b32_e32 v1, 2, v158
	v_and_b32_e32 v1, 32, v1
	v_bitop3_b32 v2, v0, s7, v1 bitop3:0xde
	v_bitop3_b32 v159, s10, v0, v1 bitop3:0xf6
	v_lshlrev_b32_e32 v0, 15, v8
	v_and_b32_e32 v0, 0xffff0000, v0
	v_lshl_add_u32 v0, v9, 12, v0
	v_and_b32_e32 v1, 1, v8
	v_lshl_or_b32 v0, v1, 6, v0
	v_lshl_add_u32 v140, v10, 1, v0
	v_lshlrev_b32_e32 v0, 15, v11
	v_and_b32_e32 v0, 0xffff0000, v0
	s_waitcnt vmcnt(6)
	s_cmpk_lt_u32 s6, 0x100
	v_lshl_add_u32 v0, v12, 12, v0
	v_and_b32_e32 v1, 1, v11
	s_cselect_b64 s[6:7], -1, 0
	v_lshl_or_b32 v0, v1, 6, v0
	s_add_i32 s36, 0, 0x10000
	s_add_i32 s37, 0, 0x14000
	v_mov_b32_e32 v141, v135
	v_lshl_add_u32 v142, v13, 1, v0
	v_mov_b32_e32 v143, v135
	v_add_u32_e32 v160, s36, v159
	v_add_u32_e32 v161, s37, v159
	v_add_u32_e32 v162, 0, v2
	s_mov_b32 s38, 0xa0000
	s_mov_b64 s[8:9], 0xb0000
	s_mov_b32 s39, 0xb0000
	s_mov_b64 s[12:13], s[18:19]
	s_mov_b64 s[10:11], s[16:17]
	s_barrier
	s_branch .LBB0_471

.LBB0_610:
	s_lshl_b32 s10, s10, 5
	s_mov_b64 s[18:19], 0x80
	s_and_b32 s54, s10, 0x60
	s_add_i32 m0, s27, 0x18000
	v_lshl_add_u64 v[8:9], v[8:9], 0, s[18:19]
	s_lshl_b32 s51, s5, 6
	s_lshl_b32 s5, s5, 13
	s_lshl_b32 s13, s54, 7
	global_load_lds_dwordx4 v[8:9], off
	v_lshl_add_u64 v[6:7], v[6:7], 0, s[18:19]
	s_add_i32 m0, s27, 0x1a000
	s_add_i32 s55, s27, 0x8000
	s_add_i32 s65, s27, 0xa000
	global_load_lds_dwordx4 v[6:7], off
	v_lshl_add_u64 v[2:3], v[2:3], 0, s[18:19]
	s_mov_b32 m0, s55
	s_add_u32 s10, s6, 0x80080
	global_load_lds_dwordx4 v[2:3], off
	v_lshl_add_u64 v[2:3], v[4:5], 0, s[18:19]
	s_mov_b32 m0, s65
	s_addc_u32 s11, s7, 0
	global_load_lds_dwordx4 v[2:3], off
	s_add_i32 m0, s27, 0x1c000
	v_lshl_add_u64 v[2:3], s[10:11], 0, v[198:199]
	global_load_lds_dwordx4 v[2:3], off
	v_lshl_add_u64 v[2:3], s[10:11], 0, v[202:203]
	s_add_i32 m0, s27, 0x1e000
	s_movk_i32 s10, 0x3c0
	global_load_lds_dwordx4 v[2:3], off
	s_waitcnt vmcnt(8)
	s_barrier
	v_and_b32_e32 v2, 48, v220
	v_lshlrev_b32_e32 v3, 6, v220
	v_and_or_b32 v2, v3, s10, v2
	v_lshlrev_b32_e32 v3, 2, v220
	v_and_b32_e32 v3, 32, v3
	v_bitop3_b32 v4, v2, s5, v3 bitop3:0xde
	v_bitop3_b32 v221, s13, v2, v3 bitop3:0xf6
	v_lshlrev_b32_e32 v2, 15, v1
	v_and_b32_e32 v2, 0xffff0000, v2
	v_lshl_add_u32 v2, v10, 12, v2
	v_and_b32_e32 v1, 1, v1
	v_lshl_or_b32 v1, v1, 6, v2
	v_lshl_add_u32 v2, v11, 1, v1
	v_lshlrev_b32_e32 v1, 15, v12
	s_mov_b64 s[10:11], 0x80080
	v_mov_b32_e32 v3, v0
	v_and_b32_e32 v1, 0xffff0000, v1
	s_cmpk_lt_u32 s12, 0x100
	v_lshl_add_u64 v[204:205], v[2:3], 0, s[10:11]
	v_lshl_add_u32 v1, v13, 12, v1
	v_and_b32_e32 v2, 1, v12
	s_waitcnt vmcnt(6)
	s_cselect_b64 s[20:21], -1, 0
	s_cmp_eq_u64 s[60:61], 0
	v_lshl_or_b32 v1, v2, 6, v1
	s_cselect_b64 s[22:23], -1, 0
	s_cmp_lg_u64 s[60:61], 0
	v_lshl_add_u32 v2, v14, 1, v1
	s_cselect_b64 s[24:25], -1, 0
	v_lshl_add_u64 v[206:207], v[2:3], 0, s[10:11]
	s_mov_b32 s26, 0x3a800000
	s_mov_b32 s28, 0x358637bd
	s_mov_b32 s66, 0x800000
	s_mov_b32 s30, 0x45800000
	s_add_i32 s67, 0, 0x10000
	s_add_i32 s68, 0, 0x14000
	v_add_u32_e32 v222, 0, v4
	v_mov_b32_e32 v223, 0x358637bd
	s_mov_b64 s[38:39], s[0:1]
	s_mov_b64 s[46:47], s[6:7]
	s_barrier
	s_branch .LBB0_613

.LBB0_797:
	s_and_b32 s26, s15, 3
	v_and_b32_e32 v14, 48, v140
	v_lshlrev_b32_e32 v15, 6, v140
	s_movk_i32 s15, 0x3c0
	v_and_or_b32 v14, v15, s15, v14
	v_lshlrev_b32_e32 v15, 2, v140
	s_lshl_b32 s1, s14, 6
	s_lshl_b32 s14, s14, 13
	v_and_b32_e32 v15, 32, v15
	v_bitop3_b32 v16, v14, s14, v15 bitop3:0xde
	s_lshl_b32 s14, s26, 12
	v_bitop3_b32 v141, v14, s14, v15 bitop3:0xde
	s_mov_b64 s[14:15], 0x80
	s_add_i32 m0, s3, 0x18000
	v_lshl_add_u64 v[6:7], v[6:7], 0, s[14:15]
	global_load_lds_dwordx4 v[6:7], off
	v_lshl_add_u64 v[4:5], v[4:5], 0, s[14:15]
	s_add_i32 m0, s3, 0x1a000
	s_add_i32 s31, s3, 0x8000
	s_add_i32 s33, s3, 0xa000
	global_load_lds_dwordx4 v[4:5], off
	v_lshl_add_u64 v[0:1], v[0:1], 0, s[14:15]
	s_mov_b32 m0, s31
	s_add_u32 s22, s6, 0x80080
	global_load_lds_dwordx4 v[0:1], off
	v_lshl_add_u64 v[0:1], v[2:3], 0, s[14:15]
	s_mov_b32 m0, s33
	s_addc_u32 s23, s7, 0
	global_load_lds_dwordx4 v[0:1], off
	s_add_i32 m0, s3, 0x1c000
	v_lshl_add_u64 v[0:1], s[22:23], 0, v[132:133]
	global_load_lds_dwordx4 v[0:1], off
	v_lshl_add_u64 v[0:1], s[22:23], 0, v[128:129]
	s_add_i32 m0, s3, 0x1e000
	s_cmpk_lt_u32 s16, 0x100
	global_load_lds_dwordx4 v[0:1], off
	s_waitcnt vmcnt(8)
	s_barrier
	v_lshlrev_b32_e32 v0, 15, v12
	v_and_b32_e32 v0, 0xffff0000, v0
	v_lshl_add_u32 v0, v11, 12, v0
	v_and_b32_e32 v1, 1, v12
	s_cselect_b64 s[16:17], -1, 0
	s_add_u32 s18, s60, s18
	v_lshl_or_b32 v0, v1, 6, v0
	s_addc_u32 s19, s61, s19
	v_lshl_add_u32 v0, v13, 1, v0
	v_mov_b32_e32 v1, v133
	v_lshl_add_u64 v[0:1], s[18:19], 0, v[0:1]
	s_mov_b64 s[22:23], 0x19880080
	v_lshl_add_u64 v[136:137], v[0:1], 0, s[22:23]
	v_lshlrev_b32_e32 v0, 15, v8
	v_and_b32_e32 v0, 0xffff0000, v0
	v_lshl_add_u32 v0, v9, 12, v0
	v_and_b32_e32 v1, 1, v8
	v_lshl_or_b32 v0, v1, 6, v0
	v_lshl_add_u32 v0, v10, 1, v0
	v_mov_b32_e32 v1, v133
	v_lshl_add_u64 v[0:1], s[18:19], 0, v[0:1]
	v_lshl_add_u64 v[138:139], v[0:1], 0, s[22:23]
	s_add_i32 s22, s21, s2
	s_ashr_i32 s23, s22, 31
	s_lshl_b64 s[22:23], s[22:23], 12
	s_add_u32 s21, s60, s22
	s_addc_u32 s22, s61, s23
	s_add_u32 s34, s21, 0x1d800100
	s_waitcnt vmcnt(6)
	s_addc_u32 s35, s22, 0
	s_add_i32 s36, 0, 0x10000
	s_add_i32 s37, 0, 0x14000
	s_add_i32 s48, 0, 0x18000
	s_add_i32 s49, 0, 0x1c000
	s_add_i32 s40, s36, s20
	s_add_i32 s46, s37, s20
	s_add_i32 s50, s48, s20
	s_add_i32 s52, s49, s20
	s_mov_b32 s30, 0
	v_add_u32_e32 v142, 0, v16
	s_add_i32 s38, s3, 0xc000
	s_add_i32 s39, s3, 0xe000
	s_add_i32 s41, s40, 0x2000
	s_add_i32 s47, s46, 0x2000
	s_add_i32 s51, s50, 0x2000
	s_add_i32 s53, s52, 0x2000
	v_mov_b32_e32 v0, v133
	v_mov_b32_e32 v1, v133
	v_mov_b32_e32 v2, v133
	v_mov_b32_e32 v3, v133
	v_mov_b32_e32 v4, v133
	v_mov_b32_e32 v5, v133
	v_mov_b32_e32 v6, v133
	v_mov_b32_e32 v7, v133
	v_mov_b32_e32 v12, v133
	v_mov_b32_e32 v13, v133
	v_mov_b32_e32 v14, v133
	v_mov_b32_e32 v15, v133
	v_mov_b32_e32 v20, v133
	v_mov_b32_e32 v21, v133
	v_mov_b32_e32 v22, v133
	v_mov_b32_e32 v23, v133
	v_mov_b32_e32 v32, v133
	v_mov_b32_e32 v33, v133
	v_mov_b32_e32 v34, v133
	v_mov_b32_e32 v35, v133
	v_mov_b32_e32 v36, v133
	v_mov_b32_e32 v37, v133
	v_mov_b32_e32 v38, v133
	v_mov_b32_e32 v39, v133
	v_mov_b32_e32 v44, v133
	v_mov_b32_e32 v45, v133
	v_mov_b32_e32 v46, v133
	v_mov_b32_e32 v47, v133
	v_mov_b32_e32 v52, v133
	v_mov_b32_e32 v53, v133
	v_mov_b32_e32 v54, v133
	v_mov_b32_e32 v55, v133
	v_mov_b32_e32 v8, v133
	v_mov_b32_e32 v9, v133
	v_mov_b32_e32 v10, v133
	v_mov_b32_e32 v11, v133
	v_mov_b32_e32 v16, v133
	v_mov_b32_e32 v17, v133
	v_mov_b32_e32 v18, v133
	v_mov_b32_e32 v19, v133
	v_mov_b32_e32 v24, v133
	v_mov_b32_e32 v25, v133
	v_mov_b32_e32 v26, v133
	v_mov_b32_e32 v27, v133
	v_mov_b32_e32 v28, v133
	v_mov_b32_e32 v29, v133
	v_mov_b32_e32 v30, v133
	v_mov_b32_e32 v31, v133
	v_mov_b32_e32 v40, v133
	v_mov_b32_e32 v41, v133
	v_mov_b32_e32 v42, v133
	v_mov_b32_e32 v43, v133
	v_mov_b32_e32 v48, v133
	v_mov_b32_e32 v49, v133
	v_mov_b32_e32 v50, v133
	v_mov_b32_e32 v51, v133
	v_mov_b32_e32 v56, v133
	v_mov_b32_e32 v57, v133
	v_mov_b32_e32 v58, v133
	v_mov_b32_e32 v59, v133
	v_mov_b32_e32 v60, v133
	v_mov_b32_e32 v61, v133
	v_mov_b32_e32 v62, v133
	v_mov_b32_e32 v63, v133
	v_mov_b32_e32 v64, v133
	v_mov_b32_e32 v65, v133
	v_mov_b32_e32 v66, v133
	v_mov_b32_e32 v67, v133
	v_mov_b32_e32 v68, v133
	v_mov_b32_e32 v69, v133
	v_mov_b32_e32 v70, v133
	v_mov_b32_e32 v71, v133
	v_mov_b32_e32 v76, v133
	v_mov_b32_e32 v77, v133
	v_mov_b32_e32 v78, v133
	v_mov_b32_e32 v79, v133
	v_mov_b32_e32 v84, v133
	v_mov_b32_e32 v85, v133
	v_mov_b32_e32 v86, v133
	v_mov_b32_e32 v87, v133
	v_mov_b32_e32 v96, v133
	v_mov_b32_e32 v97, v133
	v_mov_b32_e32 v98, v133
	v_mov_b32_e32 v99, v133
	v_mov_b32_e32 v100, v133
	v_mov_b32_e32 v101, v133
	v_mov_b32_e32 v102, v133
	v_mov_b32_e32 v103, v133
	v_mov_b32_e32 v112, v133
	v_mov_b32_e32 v113, v133
	v_mov_b32_e32 v114, v133
	v_mov_b32_e32 v115, v133
	v_mov_b32_e32 v116, v133
	v_mov_b32_e32 v117, v133
	v_mov_b32_e32 v118, v133
	v_mov_b32_e32 v119, v133
	v_mov_b32_e32 v72, v133
	v_mov_b32_e32 v73, v133
	v_mov_b32_e32 v74, v133
	v_mov_b32_e32 v75, v133
	v_mov_b32_e32 v80, v133
	v_mov_b32_e32 v81, v133
	v_mov_b32_e32 v82, v133
	v_mov_b32_e32 v83, v133
	v_mov_b32_e32 v88, v133
	v_mov_b32_e32 v89, v133
	v_mov_b32_e32 v90, v133
	v_mov_b32_e32 v91, v133
	v_mov_b32_e32 v92, v133
	v_mov_b32_e32 v93, v133
	v_mov_b32_e32 v94, v133
	v_mov_b32_e32 v95, v133
	v_mov_b32_e32 v104, v133
	v_mov_b32_e32 v105, v133
	v_mov_b32_e32 v106, v133
	v_mov_b32_e32 v107, v133
	v_mov_b32_e32 v108, v133
	v_mov_b32_e32 v109, v133
	v_mov_b32_e32 v110, v133
	v_mov_b32_e32 v111, v133
	v_mov_b32_e32 v120, v133
	v_mov_b32_e32 v121, v133
	v_mov_b32_e32 v122, v133
	v_mov_b32_e32 v123, v133
	v_mov_b32_e32 v124, v133
	v_mov_b32_e32 v125, v133
	v_mov_b32_e32 v126, v133
	v_mov_b32_e32 v127, v133
	s_barrier
	s_branch .LBB0_800

.LBB0_903:
	s_lshl_b32 s14, s14, 5
	s_and_b32 s37, s14, 0x60
	s_mov_b64 s[14:15], 0x80
	s_add_i32 m0, s30, 0x18000
	v_lshl_add_u64 v[6:7], v[6:7], 0, s[14:15]
	s_lshl_b32 s36, s1, 6
	s_lshl_b32 s1, s1, 13
	s_lshl_b32 s17, s37, 7
	global_load_lds_dwordx4 v[6:7], off
	v_lshl_add_u64 v[4:5], v[4:5], 0, s[14:15]
	s_add_i32 m0, s30, 0x1a000
	s_add_i32 s38, s30, 0x8000
	s_add_i32 s39, s30, 0xa000
	global_load_lds_dwordx4 v[4:5], off
	v_lshl_add_u64 v[0:1], v[0:1], 0, s[14:15]
	s_mov_b32 m0, s38
	s_add_u32 s18, s26, 0x40080
	global_load_lds_dwordx4 v[0:1], off
	v_lshl_add_u64 v[0:1], v[2:3], 0, s[14:15]
	s_mov_b32 m0, s39
	s_addc_u32 s19, s27, 0
	global_load_lds_dwordx4 v[0:1], off
	s_add_i32 m0, s30, 0x1c000
	v_lshl_add_u64 v[0:1], s[18:19], 0, v[154:155]
	global_load_lds_dwordx4 v[0:1], off
	v_lshl_add_u64 v[0:1], s[18:19], 0, v[158:159]
	s_add_i32 m0, s30, 0x1e000
	s_movk_i32 s18, 0x3c0
	global_load_lds_dwordx4 v[0:1], off
	s_waitcnt vmcnt(8)
	s_barrier
	v_and_b32_e32 v0, 48, v182
	v_lshlrev_b32_e32 v1, 6, v182
	v_and_or_b32 v0, v1, s18, v0
	v_lshlrev_b32_e32 v1, 2, v182
	v_and_b32_e32 v1, 32, v1
	v_bitop3_b32 v2, v0, s1, v1 bitop3:0xde
	v_bitop3_b32 v183, s17, v0, v1 bitop3:0xf6
	v_lshlrev_b32_e32 v0, 14, v8
	v_and_b32_e32 v0, 0xffff8000, v0
	v_lshl_add_u32 v0, v9, 11, v0
	v_and_b32_e32 v1, 1, v8
	v_lshl_or_b32 v0, v1, 6, v0
	v_lshl_add_u32 v160, v10, 1, v0
	v_lshlrev_b32_e32 v0, 14, v11
	v_and_b32_e32 v0, 0xffff8000, v0
	s_waitcnt vmcnt(6)
	s_cmpk_lt_u32 s16, 0x100
	v_lshl_add_u32 v0, v12, 11, v0
	v_and_b32_e32 v1, 1, v11
	s_cselect_b64 s[16:17], -1, 0
	v_lshl_or_b32 v0, v1, 6, v0
	s_add_i32 s40, 0, 0x10000
	s_add_i32 s41, 0, 0x14000
	v_mov_b32_e32 v161, v155
	v_lshl_add_u32 v162, v13, 1, v0
	v_mov_b32_e32 v163, v155
	v_add_u32_e32 v184, s40, v183
	v_add_u32_e32 v185, s41, v183
	v_add_u32_e32 v186, 0, v2
	v_mbcnt_hi_u32_b32 v187, -1, v219
	s_add_i32 s46, s30, 0xc000
	s_mov_b64 s[22:23], s[4:5]
	s_mov_b64 s[24:25], s[26:27]
	s_barrier
	s_branch .LBB0_906

.LBB0_995:
	s_lshl_b32 s45, s12, 6
	s_lshl_b32 s18, s12, 13
	s_lshl_b32 s5, s13, 5
	s_mov_b64 s[12:13], 0x80
	s_and_b32 s46, s5, 0x60
	s_add_i32 m0, s3, 0x18000
	v_lshl_add_u64 v[6:7], v[6:7], 0, s[12:13]
	s_lshl_b32 s19, s46, 7
	global_load_lds_dwordx4 v[6:7], off
	v_lshl_add_u64 v[4:5], v[4:5], 0, s[12:13]
	s_add_i32 m0, s3, 0x1a000
	s_add_i32 s47, s3, 0x8000
	s_add_i32 s48, s3, 0xa000
	global_load_lds_dwordx4 v[4:5], off
	v_lshl_add_u64 v[0:1], v[0:1], 0, s[12:13]
	s_mov_b32 m0, s47
	s_add_u32 s16, s36, 0x80080
	global_load_lds_dwordx4 v[0:1], off
	v_lshl_add_u64 v[0:1], v[2:3], 0, s[12:13]
	s_mov_b32 m0, s48
	s_addc_u32 s17, s37, 0
	global_load_lds_dwordx4 v[0:1], off
	s_add_i32 m0, s3, 0x1c000
	v_lshl_add_u64 v[0:1], s[16:17], 0, v[130:131]
	global_load_lds_dwordx4 v[0:1], off
	v_lshl_add_u64 v[0:1], s[16:17], 0, v[134:135]
	s_add_i32 m0, s3, 0x1e000
	s_sext_i32_i16 s5, s14
	global_load_lds_dwordx4 v[0:1], off
	s_waitcnt vmcnt(8)
	s_barrier
	v_and_b32_e32 v0, 48, v144
	v_lshlrev_b32_e32 v1, 6, v144
	s_movk_i32 s14, 0x3c0
	v_and_or_b32 v0, v1, s14, v0
	v_lshlrev_b32_e32 v1, 2, v144
	v_and_b32_e32 v1, 32, v1
	v_bitop3_b32 v2, v0, s18, v1 bitop3:0xde
	v_bitop3_b32 v145, s19, v0, v1 bitop3:0xf6
	v_lshlrev_b32_e32 v0, 15, v8
	v_and_b32_e32 v0, 0xffff0000, v0
	v_lshl_add_u32 v0, v9, 12, v0
	v_and_b32_e32 v1, 1, v8
	v_lshl_or_b32 v0, v1, 6, v0
	v_lshl_add_u32 v136, v10, 1, v0
	v_lshlrev_b32_e32 v0, 15, v11
	v_and_b32_e32 v0, 0xffff0000, v0
	s_waitcnt vmcnt(6)
	s_cmpk_lt_u32 s15, 0x100
	v_lshl_add_u32 v0, v12, 12, v0
	v_and_b32_e32 v1, 1, v11
	s_cselect_b64 s[14:15], -1, 0
	v_lshl_or_b32 v0, v1, 6, v0
	s_add_i32 s49, 0, 0x10000
	s_add_i32 s50, 0, 0x14000
	v_mov_b32_e32 v137, v131
	v_lshl_add_u32 v138, v13, 1, v0
	v_mov_b32_e32 v139, v131
	v_add_u32_e32 v146, s49, v145
	v_add_u32_e32 v147, s50, v145
	v_add_u32_e32 v148, 0, v2
	v_mov_b32_e32 v149, 0x358637bd
	s_mov_b32 s51, 0x800000
	s_mov_b64 s[16:17], 0x200000
	s_mov_b32 s52, 0x200000
	s_mov_b64 s[18:19], 0x240000
	s_mov_b32 s53, 0x240000
	s_mov_b64 s[20:21], 0x280000
	s_mov_b32 s54, 0x280000
	s_mov_b64 s[22:23], 0x2c0000
	s_mov_b32 s55, 0x2c0000
	s_mov_b64 s[28:29], s[34:35]
	s_mov_b64 s[30:31], s[36:37]
	s_barrier
	s_branch .LBB0_998

.LBB0_1071:
	s_lshl_b32 s38, s4, 6
	s_lshl_b32 s12, s4, 13
	s_lshl_b32 s4, s5, 5
	s_and_b32 s39, s4, 0x60
	s_mov_b64 s[4:5], 0x80
	s_add_i32 m0, s3, 0x18000
	v_lshl_add_u64 v[6:7], v[6:7], 0, s[4:5]
	s_lshl_b32 s13, s39, 7
	global_load_lds_dwordx4 v[6:7], off
	v_lshl_add_u64 v[4:5], v[4:5], 0, s[4:5]
	s_add_i32 m0, s3, 0x1a000
	s_add_i32 s40, s3, 0x8000
	s_add_i32 s41, s3, 0xa000
	global_load_lds_dwordx4 v[4:5], off
	v_lshl_add_u64 v[0:1], v[0:1], 0, s[4:5]
	s_mov_b32 m0, s40
	s_add_u32 s8, s30, 0x200080
	global_load_lds_dwordx4 v[0:1], off
	v_lshl_add_u64 v[0:1], v[2:3], 0, s[4:5]
	s_mov_b32 m0, s41
	s_addc_u32 s9, s31, 0
	global_load_lds_dwordx4 v[0:1], off
	s_add_i32 m0, s3, 0x1c000
	v_lshl_add_u64 v[0:1], s[8:9], 0, v[138:139]
	global_load_lds_dwordx4 v[0:1], off
	v_lshl_add_u64 v[0:1], s[8:9], 0, v[142:143]
	s_add_i32 m0, s3, 0x1e000
	s_sext_i32_i8 s42, s6
	global_load_lds_dwordx4 v[0:1], off
	s_waitcnt vmcnt(8)
	s_barrier
	v_and_b32_e32 v0, 48, v154
	v_lshlrev_b32_e32 v1, 6, v154
	s_movk_i32 s6, 0x3c0
	v_and_or_b32 v0, v1, s6, v0
	v_lshlrev_b32_e32 v1, 2, v154
	v_and_b32_e32 v1, 32, v1
	v_bitop3_b32 v2, v0, s12, v1 bitop3:0xde
	v_bitop3_b32 v155, s13, v0, v1 bitop3:0xf6
	v_lshlrev_b32_e32 v0, 17, v8
	v_and_b32_e32 v0, 0xfffc0000, v0
	v_lshl_add_u32 v0, v9, 14, v0
	v_and_b32_e32 v1, 1, v8
	v_lshl_or_b32 v0, v1, 6, v0
	v_lshl_add_u32 v144, v10, 1, v0
	v_lshlrev_b32_e32 v0, 17, v11
	v_and_b32_e32 v0, 0xfffc0000, v0
	s_waitcnt vmcnt(6)
	s_cmpk_lt_u32 s7, 0x100
	v_lshl_add_u32 v0, v12, 14, v0
	v_and_b32_e32 v1, 1, v11
	s_cselect_b64 s[6:7], -1, 0
	v_lshl_or_b32 v0, v1, 6, v0
	s_add_i32 s44, 0, 0x10000
	s_add_i32 s45, 0, 0x14000
	v_mov_b32_e32 v145, v139
	v_lshl_add_u32 v146, v13, 1, v0
	v_mov_b32_e32 v147, v139
	v_add_u32_e32 v156, s44, v155
	v_add_u32_e32 v157, s45, v155
	v_add_u32_e32 v158, 0, v2
	s_mov_b64 s[8:9], 0x80000
	s_mov_b32 s46, 0x80000
	s_mov_b64 s[12:13], 0x90000
	s_mov_b32 s47, 0x90000
	s_mov_b64 s[14:15], 0xa0000
	s_mov_b32 s48, 0xa0000
	s_mov_b64 s[16:17], 0xb0000
	s_mov_b32 s49, 0xb0000
	s_mov_b64 s[22:23], s[28:29]
	s_mov_b64 s[24:25], s[30:31]
	s_barrier
	s_branch .LBB0_1074
